# conv4 tail: chunk dequeue one chunk ahead (issued after the panel poll)
# speedup vs baseline: 1.0049x; 1.0049x over previous
.LBB0_152:
	v_mov_b32_e32 v42, v153
	v_readlane_b32 s36, v254, 4
	v_lshlrev_b32_e32 v0, 3, v42
	v_and_b32_e32 v92, 0x3f8, v0
	v_mov_b32_e32 v95, 0
	v_lshlrev_b32_e32 v94, 2, v92
	v_readlane_b32 s42, v254, 10
	v_readlane_b32 s43, v254, 11
	s_mov_b64 s[0:1], 0x1000
	v_readlane_b32 s44, v254, 12
	v_lshl_add_u64 v[16:17], s[42:43], 0, v[94:95]
	v_lshl_add_u64 v[8:9], v[16:17], 0, s[0:1]
	s_movk_i32 s0, 0x2000
	v_add_co_u32_e32 v4, vcc, s0, v16
	s_mov_b64 s[0:1], 0x2000
	v_lshl_add_u64 v[12:13], v[16:17], 0, s[0:1]
	s_mov_b64 s[0:1], 0x3000
	v_addc_co_u32_e32 v5, vcc, 0, v17, vcc
	v_lshl_add_u64 v[20:21], v[16:17], 0, s[0:1]
	s_movk_i32 s0, 0x3000
	v_add_co_u32_e32 v16, vcc, s0, v16
	v_readlane_b32 s45, v254, 13
	s_nop 0
	v_addc_co_u32_e32 v17, vcc, 0, v17, vcc
	global_load_dwordx4 v[0:3], v[4:5], off offset:-4096
	s_nop 0
	global_load_dwordx4 v[4:7], v[4:5], off
	s_nop 0
	global_load_dwordx4 v[8:11], v[8:9], off offset:16
	s_nop 0
	global_load_dwordx4 v[12:15], v[12:13], off offset:16
	s_nop 0
	global_load_dwordx4 v[16:19], v[16:17], off
	s_nop 0
	global_load_dwordx4 v[20:23], v[20:21], off offset:16
	s_nop 0
	global_load_dwordx4 v[24:27], v94, s[42:43]
	global_load_dwordx4 v[28:31], v94, s[44:45]
	global_load_dwordx4 v[32:35], v94, s[42:43] offset:16
	global_load_dwordx4 v[36:39], v94, s[44:45] offset:16
	v_or_b32_e32 v40, s91, v152
	v_cmp_eq_u32_e64 s[0:1], 0, v40
	v_lshlrev_b32_e32 v40, 1, v92
	v_mov_b32_e32 v41, v95
	v_readlane_b32 s37, v254, 5
	v_readlane_b32 s38, v254, 6
	v_readlane_b32 s39, v254, 7
	v_readlane_b32 s40, v254, 8
	v_readlane_b32 s41, v254, 9
	v_readlane_b32 s46, v254, 14
	v_readlane_b32 s47, v254, 15
	v_readlane_b32 s48, v254, 16
	v_readlane_b32 s49, v254, 17
	v_readlane_b32 s50, v254, 18
	v_readlane_b32 s51, v254, 19
	v_writelane_b32 v254, s0, 39
	v_lshl_add_u64 v[98:99], s[34:35], 0, v[40:41]
	v_lshl_add_u64 v[100:101], s[30:31], 0, v[40:41]
	v_ashrrev_i32_e32 v40, 4, v42
	v_writelane_b32 v254, s1, 40
	s_add_u32 s6, s24, 0x74000
	v_ashrrev_i32_e32 v93, 7, v42
	v_and_b32_e32 v119, -8, v40
	v_lshl_add_u64 v[40:41], s[22:23], 0, v[94:95]
	s_mov_b64 s[0:1], 0x4200000
	s_addc_u32 s7, s25, 0
	v_lshl_add_u64 v[96:97], s[56:57], 0, v[94:95]
	v_and_b32_e32 v118, 3, v93
	v_lshl_add_u64 v[102:103], v[40:41], 0, s[0:1]
	s_add_i32 s3, 0, 0x20080
	s_movk_i32 s86, 0x407f
	s_movk_i32 s87, 0x4080
	s_mov_b32 s88, 0xfe03f81
	s_movk_i32 s89, 0xf7f0
	s_movk_i32 s90, 0x80c
	v_mov_b32_e32 v120, 0xfffff7f3
	v_readlane_b32 s98, v254, 39
	v_readlane_b32 s99, v254, 40
	s_mov_b64 vcc, exec
	s_and_b64 exec, exec, s[98:99]
	v_mov_b32_e32 v252, 1
	global_atomic_add v252, v95, v252, s[6:7] sc0
	s_mov_b64 exec, vcc
	s_mov_b32 s99, 0
	s_branch .LBB0_156

.LBB0_156:
	s_waitcnt vmcnt(0)
	s_barrier
	s_mov_b64 s[0:1], exec
	v_readlane_b32 s8, v254, 39
	v_readlane_b32 s9, v254, 40
	s_and_b64 s[8:9], s[0:1], s[8:9]
	s_mov_b64 exec, s[8:9]
	s_cbranch_execz .LBB0_193
	s_mov_b64 s[36:37], exec
	v_mbcnt_lo_u32_b32 v40, s36, 0
	v_mbcnt_hi_u32_b32 v40, s37, v40
	v_cmp_eq_u32_e32 vcc, 0, v40
	s_and_saveexec_b64 s[14:15], vcc
	s_cbranch_execz .LBB0_159
	s_bcnt1_i32_b64 s8, s[36:37]
	v_mov_b32_e32 v41, v252

.LBB0_192:
	s_or_b64 exec, exec, s[14:15]
	v_mov_b32_e32 v252, 1
	global_atomic_add v252, v95, v252, s[6:7] sc0
	v_mov_b32_e32 v40, s3
	ds_write_b32 v40, v42
